# ctx mini-GEMM retiled: 32x32 per wave, 4 waves/CU, 8 k-steps in flight (was 32x64, 2 waves, 4 steps)
# speedup vs baseline: 1.0052x; 1.0052x over previous
; __global__ void __launch_bounds__(512) fwd_kernel(Params p) {
;     ...
;                 } else if (ph == 5) { gj.A = (kind == 0) ? HB : Ob; gj.Bt = WLp + W_WO; gj.o0 = Yb; }
;                 else if (ph == 7) { gj.Bt = WLp + W_GU; gj.N = 2 * FF; gj.epi = 2; gj.o0 = ACT; }
;                 else { gj.A = ACT; gj.Bt = WLp + W_DN; gj.K = FF; gj.o0 = HB; }
;                 if (l == 3 && ph >= 5) { gj.M = NB * SEQ; gj.skip = 1; }
;                 pg8::StaticOrder S; S.init(gj.M, gj.N, G, (bx + gj.crot) % G, gj.skip);
;                 const pg8::Gemm gg{gj.A, gj.Bt, gj.K};
;                 if (gj.epi == 0) { EpiStore E{gj.o0, gj.ldc}; pg8::gemm_phase<EpiStore, pg8::StaticOrder>(lds, gg, S, E, td); }
;                 else if (gj.epi == 1) { EpiQK E{gj.o0, (long long)(gj.o1 - gj.o0), gj.rope, gj.mode, ((gj.mode == 1) ? 0.10206207261596577f : 0.125f) * LOG2E}; pg8::gemm_phase<EpiQK, pg8::StaticOrder>(lds, gg, S, E, td); }
;                 else { EpiSwiGLU E{gj.o0}; pg8::gemm_phase<EpiSwiGLU, pg8::StaticOrder>(lds, gg, S, E, td); }
.Lcg0_go:
	v_readlane_b32 s1, v252, 7
	s_lshr_b32 s1, s1, 6
	s_cmp_ge_u32 s1, 4
	s_cbranch_scc1 .Lcg0_done
	s_mul_i32 s0, s4, 0x1880000
	s_add_u32 s8, s94, s0
	s_addc_u32 s9, s95, 0
	s_cmp_eq_u32 s5, 5
	s_mov_b32 s1, 0x1c00000
	s_cselect_b32 s0, 0x2780000, s1
	s_add_u32 s8, s8, s0
	s_addc_u32 s9, s9, 0
	s_cmp_eq_u32 s5, 5
	s_movk_i32 s1, 0xb00
	s_cselect_b32 s13, 0x400, s1
	s_mov_b32 s0, 0xb500000
	s_cmp_eq_u32 s5, 5
	s_cbranch_scc0 .Lcg0_a
	s_mov_b32 s0, 0x7300000
	s_cmp_eq_u32 s4, 0
	s_cbranch_scc1 .Lcg0_a
	s_mov_b32 s0, 0x1bd00000
	s_cmp_eq_u32 s4, 1
	s_cbranch_scc1 .Lcg0_a
	s_mov_b32 s0, 0x17b00000
.Lcg0_a:
	s_add_u32 s6, s94, s0
	s_addc_u32 s7, s95, 0
	s_cmp_eq_u32 s5, 5
	s_mov_b32 s1, 0x7300000
	s_cselect_b32 s0, 0xb500000, s1
	s_add_u32 s10, s94, s0
	s_addc_u32 s11, s95, 0
	v_writelane_b32 v2, s6, 0
	v_writelane_b32 v2, s7, 1
	v_writelane_b32 v2, s8, 2
	v_writelane_b32 v2, s9, 3
	v_writelane_b32 v2, s10, 4
	v_writelane_b32 v2, s11, 5
	v_writelane_b32 v2, s13, 6
	v_readlane_b32 s0, v252, 0
	v_readlane_b32 s1, v252, 7
	s_mul_i32 s0, s0, 4
	s_lshr_b32 s1, s1, 6
	s_add_i32 s2, s0, s1
	v_and_b32_e32 v5, 15, v171
	v_lshrrev_b32_e32 v6, 4, v171
	v_mul_lo_u32 v3, v5, s13
	v_lshlrev_b32_e32 v3, 1, v3
	v_lshl_add_u32 v3, v6, 4, v3
	v_lshlrev_b32_e32 v4, 11, v5
	v_lshl_add_u32 v4, v6, 3, v4
	v_mov_b32_e32 v7, 0
.Lcg0_tile:
	s_cmpk_ge_u32 s2, 1024
	s_cbranch_scc1 .Lcg0_done
	v_readlane_b32 s6, v2, 0
	v_readlane_b32 s7, v2, 1
	v_readlane_b32 s8, v2, 2
	v_readlane_b32 s9, v2, 3
	v_readlane_b32 s10, v2, 4
	v_readlane_b32 s11, v2, 5
	v_readlane_b32 s13, v2, 6
	s_lshr_b32 s0, s2, 5
	s_mul_i32 s0, s0, 32
	s_lshr_b32 s1, s0, 8
	s_and_b32 s0, s0, 0xff
	s_mul_i32 s1, s1, 0x2100
	s_add_i32 s0, s0, s1
	s_lshl_b32 s1, s0, 11
	s_add_u32 s10, s10, s1
	s_addc_u32 s11, s11, 0
	s_and_b32 s1, s2, 31
	s_mul_i32 s1, s1, 64
	s_add_u32 s10, s10, s1
	s_addc_u32 s11, s11, 0
	s_mul_i32 s1, s0, s13
	s_lshl_b32 s1, s1, 1
	s_add_u32 s6, s6, s1
	s_addc_u32 s7, s7, 0
	s_and_b32 s1, s2, 31
	s_mul_i32 s1, s1, 64
	s_mul_i32 s1, s1, s13
	s_add_u32 s8, s8, s1
	s_addc_u32 s9, s9, 0
	s_lshl_b32 s4, s13, 5
	s_mov_b32 s5, 0
	v_mov_b32_e32 v8, s6
	v_mov_b32_e32 v9, s7
	v_mov_b32_e32 v174, v3
	v_mov_b32_e32 v175, 0
	v_lshl_add_u64 v[8:9], s[6:7], 0, v[174:175]
	v_lshl_add_u64 v[10:11], v[8:9], 0, s[4:5]
	v_lshl_add_u64 v[12:13], s[8:9], 0, v[174:175]
	v_lshl_add_u64 v[14:15], v[12:13], 0, s[4:5]
	s_lshr_b32 s12, s13, 5
	v_mov_b32_e32 v24, 0
	v_mov_b32_e32 v25, 0
	v_mov_b32_e32 v26, 0
	v_mov_b32_e32 v27, 0
	v_mov_b32_e32 v28, 0
	v_mov_b32_e32 v29, 0
	v_mov_b32_e32 v30, 0
	v_mov_b32_e32 v31, 0
	v_mov_b32_e32 v32, 0
	v_mov_b32_e32 v33, 0
	v_mov_b32_e32 v34, 0
	v_mov_b32_e32 v35, 0
	v_mov_b32_e32 v36, 0
	v_mov_b32_e32 v37, 0
	v_mov_b32_e32 v38, 0
	v_mov_b32_e32 v39, 0
	global_load_dwordx4 v[40:43], v[8:9], off offset:0
	global_load_dwordx4 v[44:47], v[10:11], off offset:0
	global_load_dwordx4 v[48:51], v[12:13], off offset:0
	global_load_dwordx4 v[52:55], v[14:15], off offset:0
	global_load_dwordx4 v[56:59], v[8:9], off offset:64
	global_load_dwordx4 v[60:63], v[10:11], off offset:64
	global_load_dwordx4 v[64:67], v[12:13], off offset:64
	global_load_dwordx4 v[68:71], v[14:15], off offset:64
	global_load_dwordx4 v[72:75], v[8:9], off offset:128
	global_load_dwordx4 v[76:79], v[10:11], off offset:128
	global_load_dwordx4 v[80:83], v[12:13], off offset:128
	global_load_dwordx4 v[84:87], v[14:15], off offset:128
	global_load_dwordx4 v[88:91], v[8:9], off offset:192
	global_load_dwordx4 v[92:95], v[10:11], off offset:192
	global_load_dwordx4 v[96:99], v[12:13], off offset:192
	global_load_dwordx4 v[100:103], v[14:15], off offset:192
	global_load_dwordx4 v[104:107], v[8:9], off offset:256
	global_load_dwordx4 v[108:111], v[10:11], off offset:256
	global_load_dwordx4 v[112:115], v[12:13], off offset:256
	global_load_dwordx4 v[116:119], v[14:15], off offset:256
	global_load_dwordx4 v[120:123], v[8:9], off offset:320
	global_load_dwordx4 v[124:127], v[10:11], off offset:320
	global_load_dwordx4 v[128:131], v[12:13], off offset:320
	global_load_dwordx4 v[132:135], v[14:15], off offset:320
	global_load_dwordx4 v[136:139], v[8:9], off offset:384
	global_load_dwordx4 v[140:143], v[10:11], off offset:384
	global_load_dwordx4 v[144:147], v[12:13], off offset:384
	global_load_dwordx4 v[148:151], v[14:15], off offset:384
	global_load_dwordx4 v[152:155], v[8:9], off offset:448
	global_load_dwordx4 v[156:159], v[10:11], off offset:448
	global_load_dwordx4 v[160:163], v[12:13], off offset:448
	global_load_dwordx4 v[164:167], v[14:15], off offset:448
	s_mov_b64 s[0:1], 512
	s_sub_i32 s12, s12, 8
; __global__ void __launch_bounds__(512) fwd_kernel(Params p) {
;     ...
;                 } else if (ph == 5) { gj.A = (kind == 0) ? HB : Ob; gj.Bt = WLp + W_WO; gj.o0 = Yb; }
;                 else if (ph == 7) { gj.Bt = WLp + W_GU; gj.N = 2 * FF; gj.epi = 2; gj.o0 = ACT; }
;                 else { gj.A = ACT; gj.Bt = WLp + W_DN; gj.K = FF; gj.o0 = HB; }
;                 if (l == 3 && ph >= 5) { gj.M = NB * SEQ; gj.skip = 1; }
;                 pg8::StaticOrder S; S.init(gj.M, gj.N, G, (bx + gj.crot) % G, gj.skip);
;                 const pg8::Gemm gg{gj.A, gj.Bt, gj.K};
;                 if (gj.epi == 0) { EpiStore E{gj.o0, gj.ldc}; pg8::gemm_phase<EpiStore, pg8::StaticOrder>(lds, gg, S, E, td); }
;                 else if (gj.epi == 1) { EpiQK E{gj.o0, (long long)(gj.o1 - gj.o0), gj.rope, gj.mode, ((gj.mode == 1) ? 0.10206207261596577f : 0.125f) * LOG2E}; pg8::gemm_phase<EpiQK, pg8::StaticOrder>(lds, gg, S, E, td); }
;                 else { EpiSwiGLU E{gj.o0}; pg8::gemm_phase<EpiSwiGLU, pg8::StaticOrder>(lds, gg, S, E, td); }
.Lcg0_grp:
	v_lshl_add_u64 v[8:9], v[8:9], 0, s[0:1]
	v_lshl_add_u64 v[10:11], v[10:11], 0, s[0:1]
	v_lshl_add_u64 v[12:13], v[12:13], 0, s[0:1]
	v_lshl_add_u64 v[14:15], v[14:15], 0, s[0:1]
	s_waitcnt vmcnt(28)
	v_mfma_f32_16x16x32_bf16 v[24:27], v[48:51], v[40:43], v[24:27]
	v_mfma_f32_16x16x32_bf16 v[28:31], v[52:55], v[40:43], v[28:31]
	v_mfma_f32_16x16x32_bf16 v[32:35], v[48:51], v[44:47], v[32:35]
	v_mfma_f32_16x16x32_bf16 v[36:39], v[52:55], v[44:47], v[36:39]
	global_load_dwordx4 v[40:43], v[8:9], off offset:0
	global_load_dwordx4 v[44:47], v[10:11], off offset:0
	global_load_dwordx4 v[48:51], v[12:13], off offset:0
	global_load_dwordx4 v[52:55], v[14:15], off offset:0
	s_waitcnt vmcnt(28)
	v_mfma_f32_16x16x32_bf16 v[24:27], v[64:67], v[56:59], v[24:27]
	v_mfma_f32_16x16x32_bf16 v[28:31], v[68:71], v[56:59], v[28:31]
	v_mfma_f32_16x16x32_bf16 v[32:35], v[64:67], v[60:63], v[32:35]
	v_mfma_f32_16x16x32_bf16 v[36:39], v[68:71], v[60:63], v[36:39]
	global_load_dwordx4 v[56:59], v[8:9], off offset:64
	global_load_dwordx4 v[60:63], v[10:11], off offset:64
	global_load_dwordx4 v[64:67], v[12:13], off offset:64
	global_load_dwordx4 v[68:71], v[14:15], off offset:64
	s_waitcnt vmcnt(28)
	v_mfma_f32_16x16x32_bf16 v[24:27], v[80:83], v[72:75], v[24:27]
	v_mfma_f32_16x16x32_bf16 v[28:31], v[84:87], v[72:75], v[28:31]
	v_mfma_f32_16x16x32_bf16 v[32:35], v[80:83], v[76:79], v[32:35]
	v_mfma_f32_16x16x32_bf16 v[36:39], v[84:87], v[76:79], v[36:39]
	global_load_dwordx4 v[72:75], v[8:9], off offset:128
	global_load_dwordx4 v[76:79], v[10:11], off offset:128
	global_load_dwordx4 v[80:83], v[12:13], off offset:128
	global_load_dwordx4 v[84:87], v[14:15], off offset:128
	s_waitcnt vmcnt(28)
	v_mfma_f32_16x16x32_bf16 v[24:27], v[96:99], v[88:91], v[24:27]
	v_mfma_f32_16x16x32_bf16 v[28:31], v[100:103], v[88:91], v[28:31]
	v_mfma_f32_16x16x32_bf16 v[32:35], v[96:99], v[92:95], v[32:35]
	v_mfma_f32_16x16x32_bf16 v[36:39], v[100:103], v[92:95], v[36:39]
	global_load_dwordx4 v[88:91], v[8:9], off offset:192
	global_load_dwordx4 v[92:95], v[10:11], off offset:192
	global_load_dwordx4 v[96:99], v[12:13], off offset:192
	global_load_dwordx4 v[100:103], v[14:15], off offset:192
	s_waitcnt vmcnt(28)
	v_mfma_f32_16x16x32_bf16 v[24:27], v[112:115], v[104:107], v[24:27]
	v_mfma_f32_16x16x32_bf16 v[28:31], v[116:119], v[104:107], v[28:31]
	v_mfma_f32_16x16x32_bf16 v[32:35], v[112:115], v[108:111], v[32:35]
	v_mfma_f32_16x16x32_bf16 v[36:39], v[116:119], v[108:111], v[36:39]
	global_load_dwordx4 v[104:107], v[8:9], off offset:256
	global_load_dwordx4 v[108:111], v[10:11], off offset:256
	global_load_dwordx4 v[112:115], v[12:13], off offset:256
	global_load_dwordx4 v[116:119], v[14:15], off offset:256
	s_waitcnt vmcnt(28)
	v_mfma_f32_16x16x32_bf16 v[24:27], v[128:131], v[120:123], v[24:27]
	v_mfma_f32_16x16x32_bf16 v[28:31], v[132:135], v[120:123], v[28:31]
	v_mfma_f32_16x16x32_bf16 v[32:35], v[128:131], v[124:127], v[32:35]
	v_mfma_f32_16x16x32_bf16 v[36:39], v[132:135], v[124:127], v[36:39]
	global_load_dwordx4 v[120:123], v[8:9], off offset:320
	global_load_dwordx4 v[124:127], v[10:11], off offset:320
	global_load_dwordx4 v[128:131], v[12:13], off offset:320
	global_load_dwordx4 v[132:135], v[14:15], off offset:320
	s_waitcnt vmcnt(28)
	v_mfma_f32_16x16x32_bf16 v[24:27], v[144:147], v[136:139], v[24:27]
	v_mfma_f32_16x16x32_bf16 v[28:31], v[148:151], v[136:139], v[28:31]
	v_mfma_f32_16x16x32_bf16 v[32:35], v[144:147], v[140:143], v[32:35]
	v_mfma_f32_16x16x32_bf16 v[36:39], v[148:151], v[140:143], v[36:39]
	global_load_dwordx4 v[136:139], v[8:9], off offset:384
	global_load_dwordx4 v[140:143], v[10:11], off offset:384
	global_load_dwordx4 v[144:147], v[12:13], off offset:384
	global_load_dwordx4 v[148:151], v[14:15], off offset:384
	s_waitcnt vmcnt(28)
	v_mfma_f32_16x16x32_bf16 v[24:27], v[160:163], v[152:155], v[24:27]
	v_mfma_f32_16x16x32_bf16 v[28:31], v[164:167], v[152:155], v[28:31]
	v_mfma_f32_16x16x32_bf16 v[32:35], v[160:163], v[156:159], v[32:35]
	v_mfma_f32_16x16x32_bf16 v[36:39], v[164:167], v[156:159], v[36:39]
	global_load_dwordx4 v[152:155], v[8:9], off offset:448
	global_load_dwordx4 v[156:159], v[10:11], off offset:448
	global_load_dwordx4 v[160:163], v[12:13], off offset:448
	global_load_dwordx4 v[164:167], v[14:15], off offset:448
	s_sub_i32 s12, s12, 8
	s_cmp_lg_u32 s12, 0
	s_cbranch_scc1 .Lcg0_grp
; __global__ void __launch_bounds__(512) fwd_kernel(Params p) {
;     ...
;                 } else if (ph == 5) { gj.A = (kind == 0) ? HB : Ob; gj.Bt = WLp + W_WO; gj.o0 = Yb; }
;                 else if (ph == 7) { gj.Bt = WLp + W_GU; gj.N = 2 * FF; gj.epi = 2; gj.o0 = ACT; }
;                 else { gj.A = ACT; gj.Bt = WLp + W_DN; gj.K = FF; gj.o0 = HB; }
;                 if (l == 3 && ph >= 5) { gj.M = NB * SEQ; gj.skip = 1; }
;                 pg8::StaticOrder S; S.init(gj.M, gj.N, G, (bx + gj.crot) % G, gj.skip);
;                 const pg8::Gemm gg{gj.A, gj.Bt, gj.K};
;                 if (gj.epi == 0) { EpiStore E{gj.o0, gj.ldc}; pg8::gemm_phase<EpiStore, pg8::StaticOrder>(lds, gg, S, E, td); }
;                 else if (gj.epi == 1) { EpiQK E{gj.o0, (long long)(gj.o1 - gj.o0), gj.rope, gj.mode, ((gj.mode == 1) ? 0.10206207261596577f : 0.125f) * LOG2E}; pg8::gemm_phase<EpiQK, pg8::StaticOrder>(lds, gg, S, E, td); }
;                 else { EpiSwiGLU E{gj.o0}; pg8::gemm_phase<EpiSwiGLU, pg8::StaticOrder>(lds, gg, S, E, td); }
	s_waitcnt vmcnt(28)
	v_mfma_f32_16x16x32_bf16 v[24:27], v[48:51], v[40:43], v[24:27]
	v_mfma_f32_16x16x32_bf16 v[28:31], v[52:55], v[40:43], v[28:31]
	v_mfma_f32_16x16x32_bf16 v[32:35], v[48:51], v[44:47], v[32:35]
	v_mfma_f32_16x16x32_bf16 v[36:39], v[52:55], v[44:47], v[36:39]
	s_waitcnt vmcnt(24)
	v_mfma_f32_16x16x32_bf16 v[24:27], v[64:67], v[56:59], v[24:27]
	v_mfma_f32_16x16x32_bf16 v[28:31], v[68:71], v[56:59], v[28:31]
	v_mfma_f32_16x16x32_bf16 v[32:35], v[64:67], v[60:63], v[32:35]
	v_mfma_f32_16x16x32_bf16 v[36:39], v[68:71], v[60:63], v[36:39]
	s_waitcnt vmcnt(20)
	v_mfma_f32_16x16x32_bf16 v[24:27], v[80:83], v[72:75], v[24:27]
	v_mfma_f32_16x16x32_bf16 v[28:31], v[84:87], v[72:75], v[28:31]
	v_mfma_f32_16x16x32_bf16 v[32:35], v[80:83], v[76:79], v[32:35]
	v_mfma_f32_16x16x32_bf16 v[36:39], v[84:87], v[76:79], v[36:39]
	s_waitcnt vmcnt(16)
	v_mfma_f32_16x16x32_bf16 v[24:27], v[96:99], v[88:91], v[24:27]
	v_mfma_f32_16x16x32_bf16 v[28:31], v[100:103], v[88:91], v[28:31]
	v_mfma_f32_16x16x32_bf16 v[32:35], v[96:99], v[92:95], v[32:35]
	v_mfma_f32_16x16x32_bf16 v[36:39], v[100:103], v[92:95], v[36:39]
	s_waitcnt vmcnt(12)
	v_mfma_f32_16x16x32_bf16 v[24:27], v[112:115], v[104:107], v[24:27]
	v_mfma_f32_16x16x32_bf16 v[28:31], v[116:119], v[104:107], v[28:31]
	v_mfma_f32_16x16x32_bf16 v[32:35], v[112:115], v[108:111], v[32:35]
	v_mfma_f32_16x16x32_bf16 v[36:39], v[116:119], v[108:111], v[36:39]
	s_waitcnt vmcnt(8)
	v_mfma_f32_16x16x32_bf16 v[24:27], v[128:131], v[120:123], v[24:27]
	v_mfma_f32_16x16x32_bf16 v[28:31], v[132:135], v[120:123], v[28:31]
	v_mfma_f32_16x16x32_bf16 v[32:35], v[128:131], v[124:127], v[32:35]
	v_mfma_f32_16x16x32_bf16 v[36:39], v[132:135], v[124:127], v[36:39]
	s_waitcnt vmcnt(4)
	v_mfma_f32_16x16x32_bf16 v[24:27], v[144:147], v[136:139], v[24:27]
	v_mfma_f32_16x16x32_bf16 v[28:31], v[148:151], v[136:139], v[28:31]
	v_mfma_f32_16x16x32_bf16 v[32:35], v[144:147], v[140:143], v[32:35]
	v_mfma_f32_16x16x32_bf16 v[36:39], v[148:151], v[140:143], v[36:39]
	s_waitcnt vmcnt(0)
	v_mfma_f32_16x16x32_bf16 v[24:27], v[160:163], v[152:155], v[24:27]
	v_mfma_f32_16x16x32_bf16 v[28:31], v[164:167], v[152:155], v[28:31]
	v_mfma_f32_16x16x32_bf16 v[32:35], v[160:163], v[156:159], v[32:35]
	v_mfma_f32_16x16x32_bf16 v[36:39], v[164:167], v[156:159], v[36:39]
	s_nop 7
	v_cvt_pk_bf16_f32 v176, v24, v25
	v_cvt_pk_bf16_f32 v177, v26, v27
	global_store_dwordx2 v4, v[176:177], s[10:11] offset:0
	s_nop 1
	v_cvt_pk_bf16_f32 v176, v28, v29
	v_cvt_pk_bf16_f32 v177, v30, v31
	global_store_dwordx2 v4, v[176:177], s[10:11] offset:32
	s_nop 1
	v_cvt_pk_bf16_f32 v176, v32, v33
	v_cvt_pk_bf16_f32 v177, v34, v35
	v_add_u32_e32 v178, 0x8000, v4
	global_store_dwordx2 v178, v[176:177], s[10:11]
	s_nop 1
	v_cvt_pk_bf16_f32 v176, v36, v37
	v_cvt_pk_bf16_f32 v177, v38, v39
	v_add_u32_e32 v178, 0x8020, v4
	global_store_dwordx2 v178, v[176:177], s[10:11]
	s_nop 1
	v_readlane_b32 s0, v252, 55
	s_mul_i32 s0, s0, 4
	s_add_i32 s2, s2, s0
	s_branch .Lcg0_tile
